# v25: v24 + the XCD-local shortcut also requires gridDim.x == 256 (the only grid for which the unit / tile maps are class-local)
# speedup vs baseline: 1.0453x; 1.0041x over previous
; __device__ __forceinline__ unsigned xb_ld(unsigned* p)              { return __hip_atomic_load(p, __ATOMIC_RELAXED, __HIP_MEMORY_SCOPE_AGENT); }
; __device__ __forceinline__ unsigned xb_add(unsigned* p, unsigned v) { return __hip_atomic_fetch_add(p, v, __ATOMIC_RELAXED, __HIP_MEMORY_SCOPE_AGENT); }
; __device__ __forceinline__ void xcd_barrier_complete(unsigned* bar, unsigned x, unsigned& nloc, unsigned& nx) {
;     const unsigned G = gridDim.x * gridDim.y * gridDim.z;
;     unsigned sum, cnt, mine, sp = 0u;
;     for (;;) {
;         sum = 0u; cnt = 0u; mine = 0u;
; #pragma unroll
;         for (unsigned j = 0; j < 16; ++j) { const unsigned c = xb_ld(&bar[XB_XCNT(j)]); sum += c; cnt += (c > 0u) ? 1u : 0u; mine = (j == x) ? c : mine; }
;         if (sum == G) break;
;         __builtin_amdgcn_s_sleep(1);
;         if ((++sp & 255u) == 0u) { if (xb_ld(&bar[XB_TMO])) break; if (sp > XB_SPIN_CAP) { atomicAdd(&bar[XB_TMO], 1u); break; } }
;     }
;     nloc = mine > 0u ? mine : 1u; nx = cnt > 0u ? cnt : 1u;
; }
; __device__ __forceinline__ void xcd_barrier(const XcdBarrier& b) {
;     asm volatile("s_waitcnt vmcnt(0)" ::: "memory");
;     __syncthreads();
;     if (threadIdx.x == 0) {
;         unsigned* bar = b.bar;
;         __builtin_amdgcn_s_waitcnt(0);
;         unsigned nloc = b.st[0], nx = b.st[1];
;         if (nloc == 0u) { xcd_barrier_complete(bar, b.x, nloc, nx); b.st[0] = nloc; b.st[1] = nx; }
;         const unsigned old = xb_add(&bar[XB_XSUB(b.x)], 1u);
;         const unsigned gen = old / nloc;
;         if (old + 1u == (gen + 1u) * nloc) {
;             __builtin_amdgcn_fence(__ATOMIC_RELEASE, "agent");
;             asm volatile("s_waitcnt vmcnt(0)" ::: "memory");
;             const unsigned og = xb_add(&bar[XB_TOP], 1u);
;             const unsigned tg = og / nx;
;             if (og + 1u == (tg + 1u) * nx) xb_add(&bar[XB_TOPGEN], 1u);
;             else XB_SPIN(xb_ld(&bar[XB_TOPGEN]) == tg, bar);
;             __builtin_amdgcn_fence(__ATOMIC_ACQUIRE, "agent");
;             xb_add(&bar[XB_XGEN(b.x)], 1u);
;             asm volatile("s_waitcnt vmcnt(0)" ::: "memory");
;         } else {
;             XB_SPIN(xb_ld(&bar[XB_XGEN(b.x)]) == gen, bar);
;             __builtin_amdgcn_fence(__ATOMIC_ACQUIRE, "agent");
;             asm volatile("s_waitcnt vmcnt(0)" ::: "memory");
;         }
.LBB0_277:
	s_add_u32 s0, s94, 0x6a00000
	s_addc_u32 s1, s95, 0
	s_add_u32 s6, s94, 0x12a00000
	s_addc_u32 s7, s95, 0
	s_add_u32 s8, s94, 0x15a00000
	s_addc_u32 s9, s95, 0
	v_writelane_b32 v252, s51, 21
	s_add_u32 s10, s94, 0x18a00000
	v_writelane_b32 v252, s0, 22
	s_addc_u32 s11, s95, 0
	s_ashr_i32 s91, s68, 31
	v_writelane_b32 v252, s1, 23
	s_lshr_b32 s0, s91, 29
	s_add_i32 s0, s68, s0
	s_ashr_i32 s12, s0, 3
	s_and_b32 s0, s0, -8
	s_sub_i32 s13, s68, s0
	s_ashr_i32 s0, s80, 31
	v_writelane_b32 v252, s0, 24
	s_add_u32 s0, s94, 0x6980200
	s_addc_u32 s1, s95, 0
	v_writelane_b32 v252, s0, 25
	s_mov_b32 s84, 0x3f803f80
	v_mov_b32_e32 v113, 0
	v_writelane_b32 v252, s1, 26
	s_add_u32 s0, s94, 0x6980400
	s_addc_u32 s1, s95, 0
	v_writelane_b32 v252, s0, 27
	v_mov_b32_e32 v198, 0x358637bd
	v_mov_b32_e32 v199, 1
	v_writelane_b32 v252, s1, 28
	s_add_u32 s0, s94, 0x6980500
	s_addc_u32 s1, s95, 0
	v_writelane_b32 v252, s0, 29
	s_mov_b32 s85, s84
	s_mov_b32 s86, s84
	v_writelane_b32 v252, s1, 30
	s_add_u32 s0, s94, 0x6980600
	s_addc_u32 s1, s95, 0
	v_writelane_b32 v252, s0, 31
	s_mov_b32 s87, s84
	v_mov_b32_e32 v200, 0xffffff60
	v_writelane_b32 v252, s1, 32
	s_add_u32 s0, s94, 0x6980700
	s_addc_u32 s1, s95, 0
	v_writelane_b32 v252, s0, 33
	v_mov_b32_e32 v201, 0x10000
	v_mov_b64_e32 v[186:187], 0x200
	v_writelane_b32 v252, s1, 34
	s_add_u32 s0, s94, 0x6980800
	s_addc_u32 s1, s95, 0
	v_writelane_b32 v252, s0, 35
	v_mov_b64_e32 v[188:189], 0x1ff
	s_nop 0
	v_writelane_b32 v252, s1, 36
	s_add_u32 s0, s94, 0x6980900
	s_addc_u32 s1, s95, 0
	v_writelane_b32 v252, s0, 37
	s_nop 1
	v_writelane_b32 v252, s1, 38
	s_add_u32 s0, s94, 0x6980a00
	s_addc_u32 s1, s95, 0
	v_writelane_b32 v252, s0, 39
	s_nop 1
	v_writelane_b32 v252, s1, 40
	s_add_u32 s0, s94, 0x6980b00
	s_addc_u32 s1, s95, 0
	v_writelane_b32 v252, s0, 41
	s_nop 1
	v_writelane_b32 v252, s1, 42
	s_add_u32 s0, s94, 0x6980c00
	s_addc_u32 s1, s95, 0
	v_writelane_b32 v252, s0, 43
	s_nop 1
	v_writelane_b32 v252, s1, 44
	s_add_u32 s0, s94, 0x6980d00
	s_addc_u32 s1, s95, 0
	v_writelane_b32 v252, s0, 45
	s_nop 1
	v_writelane_b32 v252, s1, 46
	s_add_u32 s0, s94, 0x6980e00
	s_addc_u32 s1, s95, 0
	v_writelane_b32 v252, s0, 47
	s_nop 1
	v_writelane_b32 v252, s1, 48
	s_add_u32 s0, s94, 0x6980f00
	s_addc_u32 s1, s95, 0
	v_writelane_b32 v252, s0, 49
	s_nop 1
	v_writelane_b32 v252, s1, 50
	s_add_u32 s0, s94, 0x6981000
	s_addc_u32 s1, s95, 0
	v_writelane_b32 v252, s0, 51
	s_nop 1
	v_writelane_b32 v252, s1, 52
	s_add_u32 s0, s94, 0x6981100
	s_addc_u32 s1, s95, 0
	v_writelane_b32 v252, s0, 53
	s_nop 1
	v_writelane_b32 v252, s1, 54
	s_add_u32 s0, s94, 0x6981200
	s_addc_u32 s1, s95, 0
	v_writelane_b32 v252, s0, 55
	s_nop 1
	v_writelane_b32 v252, s1, 56
	s_add_u32 s0, s94, 0x6981300
	s_addc_u32 s1, s95, 0
	v_writelane_b32 v252, s0, 57
	s_cmp_eq_u32 s48, 15
	s_nop 0
	v_writelane_b32 v252, s1, 58
	s_cselect_b64 s[0:1], -1, 0
	v_writelane_b32 v252, s0, 59
	s_cmp_eq_u32 s48, 14
	s_nop 0
	v_writelane_b32 v252, s1, 60
	s_cselect_b64 s[0:1], -1, 0
	v_writelane_b32 v252, s0, 61
	s_cmp_eq_u32 s48, 13
	s_nop 0
	v_writelane_b32 v252, s1, 62
	s_cselect_b64 s[0:1], -1, 0
	v_writelane_b32 v252, s0, 63
	s_cmp_eq_u32 s48, 12
	s_nop 0
	v_writelane_b32 v253, s1, 0
	s_cselect_b64 s[0:1], -1, 0
	v_writelane_b32 v253, s0, 1
	s_cmp_eq_u32 s48, 11
	s_nop 0
	v_writelane_b32 v253, s1, 2
	s_cselect_b64 s[0:1], -1, 0
	v_writelane_b32 v253, s0, 3
	s_cmp_eq_u32 s48, 10
	s_nop 0
	v_writelane_b32 v253, s1, 4
	s_cselect_b64 s[0:1], -1, 0
	v_writelane_b32 v253, s0, 5
	s_cmp_eq_u32 s48, 9
	s_nop 0
	v_writelane_b32 v253, s1, 6
	s_cselect_b64 s[0:1], -1, 0
	v_writelane_b32 v253, s0, 7
	s_cmp_eq_u32 s48, 8
	s_nop 0
	v_writelane_b32 v253, s1, 8
	s_cselect_b64 s[0:1], -1, 0
	v_writelane_b32 v253, s0, 9
	s_cmp_eq_u32 s48, 7
	s_nop 0
	v_writelane_b32 v253, s1, 10
	s_cselect_b64 s[0:1], -1, 0
	v_writelane_b32 v253, s0, 11
	s_cmp_eq_u32 s48, 6
	s_nop 0
	v_writelane_b32 v253, s1, 12
	s_cselect_b64 s[0:1], -1, 0
	v_writelane_b32 v253, s0, 13
	s_cmp_eq_u32 s48, 5
	s_nop 0
	v_writelane_b32 v253, s1, 14
	s_cselect_b64 s[0:1], -1, 0
	v_writelane_b32 v253, s0, 15
	s_cmp_eq_u32 s48, 4
	s_nop 0
	v_writelane_b32 v253, s1, 16
	s_cselect_b64 s[0:1], -1, 0
	v_writelane_b32 v253, s0, 17
	s_cmp_eq_u32 s48, 3
	s_nop 0
	v_writelane_b32 v253, s1, 18
	s_cselect_b64 s[0:1], -1, 0
	v_writelane_b32 v253, s0, 19
	s_cmp_eq_u32 s48, 2
	s_nop 0
	v_writelane_b32 v253, s1, 20
	s_cselect_b64 s[0:1], -1, 0
	v_writelane_b32 v253, s0, 21
	s_cmp_eq_u32 s48, 1
	s_nop 0
	v_writelane_b32 v253, s1, 22
	s_cselect_b64 s[0:1], -1, 0
	v_writelane_b32 v253, s0, 23
	s_cmp_eq_u32 s48, 0
	s_nop 0
	v_writelane_b32 v253, s1, 24
	s_cselect_b64 s[0:1], -1, 0
	v_writelane_b32 v253, s0, 25
	s_nop 1
	v_writelane_b32 v253, s1, 26
	s_lshl_b32 s0, s48, 8
	s_add_u32 s0, s2, s0
	s_addc_u32 s1, s3, 0
	s_add_u32 s2, s0, 0x1400
	s_addc_u32 s3, s1, 0
	v_writelane_b32 v253, s2, 27
	s_add_u32 s0, s0, 0x2400
	s_addc_u32 s1, s1, 0
	v_writelane_b32 v253, s3, 28
	v_writelane_b32 v253, s0, 29
	s_nop 1
	v_writelane_b32 v253, s1, 30
	s_add_u32 s0, s94, 0x6983400
	s_addc_u32 s1, s95, 0
	v_writelane_b32 v253, s0, 31
	s_nop 1
	v_writelane_b32 v253, s1, 32
	s_add_u32 s0, s94, 0x6983500
	s_addc_u32 s1, s95, 0
	v_writelane_b32 v253, s0, 33
	s_cmpk_lt_i32 s68, 0x400
	s_nop 0
	v_writelane_b32 v253, s1, 34
	s_cselect_b64 s[0:1], -1, 0
	v_writelane_b32 v253, s0, 35
	s_cmpk_lg_i32 s80, 0x100
	s_nop 0
	v_writelane_b32 v253, s1, 36
	s_cselect_b64 s[0:1], -1, 0
	v_writelane_b32 v253, s0, 37
	s_nop 1
	v_writelane_b32 v253, s1, 38
	s_lshl_b32 s0, s68, 7
	s_lshr_b32 s1, s68, 3
	s_and_b32 s0, s0, 0x380
; #define LAS __attribute__((address_space(3)))
; __device__ __forceinline__ unsigned xb_ld(unsigned* p)              { return __hip_atomic_load(p, __ATOMIC_RELAXED, __HIP_MEMORY_SCOPE_AGENT); }
; __device__ __forceinline__ unsigned xb_add(unsigned* p, unsigned v) { return __hip_atomic_fetch_add(p, v, __ATOMIC_RELAXED, __HIP_MEMORY_SCOPE_AGENT); }
; __device__ __forceinline__ unsigned xb_xcc_id() { return (unsigned)__builtin_amdgcn_s_getreg((3 << 11) | 20) & 0xFu; }
; __device__ __forceinline__ XcdBarrier xcd_barrier_post(unsigned* bar, volatile LAS unsigned* st) {
;     XcdBarrier b; b.bar = bar; b.x = xb_xcc_id(); b.st = st;
;     if (threadIdx.x == 0) (void)xb_add(&bar[XB_XCNT(b.x)], 1u);
;     return b;
; }
; __device__ __forceinline__ void xcd_barrier_complete(unsigned* bar, unsigned x, unsigned& nloc, unsigned& nx) {
;     const unsigned G = gridDim.x * gridDim.y * gridDim.z;
;     unsigned sum, cnt, mine, sp = 0u;
;     for (;;) {
;         sum = 0u; cnt = 0u; mine = 0u;
; #pragma unroll
;         for (unsigned j = 0; j < 16; ++j) { const unsigned c = xb_ld(&bar[XB_XCNT(j)]); sum += c; cnt += (c > 0u) ? 1u : 0u; mine = (j == x) ? c : mine; }
;         if (sum == G) break;
;         __builtin_amdgcn_s_sleep(1);
;         if ((++sp & 255u) == 0u) { if (xb_ld(&bar[XB_TMO])) break; if (sp > XB_SPIN_CAP) { atomicAdd(&bar[XB_TMO], 1u); break; } }
;     }
;     nloc = mine > 0u ? mine : 1u; nx = cnt > 0u ? cnt : 1u;
; }
; __device__ __forceinline__ void xcd_barrier(const XcdBarrier& b) {
;     asm volatile("s_waitcnt vmcnt(0)" ::: "memory");
;     __syncthreads();
;     if (threadIdx.x == 0) {
;         unsigned* bar = b.bar;
;         __builtin_amdgcn_s_waitcnt(0);
;         unsigned nloc = b.st[0], nx = b.st[1];
;         if (nloc == 0u) { xcd_barrier_complete(bar, b.x, nloc, nx); b.st[0] = nloc; b.st[1] = nx; }
	s_and_b32 s1, s1, 0x1fffffe0
	s_add_i32 s0, s0, s1
	s_bfe_u32 s1, s68, 0x50003
	s_or_b32 s2, s0, s1
	s_cmpk_eq_i32 s80, 0x100
	s_cselect_b64 s[0:1], -1, 0
	v_writelane_b32 v253, s0, 39
	s_nop 1
	v_writelane_b32 v253, s1, 40
	s_and_b64 s[0:1], s[0:1], exec
	s_cselect_b32 s4, s2, s68
	s_ashr_i32 s5, s4, 31
	s_lshr_b32 s0, s5, 27
	s_add_i32 s0, s4, s0
	s_ashr_i32 s1, s0, 5
	s_lshr_b32 s2, s1, 30
	s_add_i32 s2, s1, s2
	s_and_b32 s2, s2, 0x3fffffc
	s_sub_i32 s2, s1, s2
	s_and_b32 s0, s0, 0x1ffffe0
	s_lshr_b32 s1, s5, 25
	s_sub_i32 s0, s4, s0
	s_add_i32 s1, s4, s1
	s_lshl_b32 s2, s2, 6
	s_lshl_b32 s14, s0, 7
	s_ashr_i32 s0, s1, 7
	s_ashr_i32 s3, s2, 31
	s_ashr_i32 s1, s0, 31
	s_lshl_b64 s[2:3], s[2:3], 1
	s_add_u32 s16, s6, s2
	s_addc_u32 s17, s7, s3
	v_writelane_b32 v253, s16, 41
	s_add_u32 s2, s8, s2
	s_addc_u32 s3, s9, s3
	v_writelane_b32 v253, s17, 42
	v_writelane_b32 v253, s2, 43
	s_nop 1
	v_writelane_b32 v253, s3, 44
	s_add_i32 s2, s14, 0xffffff80
	v_writelane_b32 v253, s2, 45
	s_sub_i32 s2, s14, 64
	v_writelane_b32 v253, s2, 46
	s_or_b32 s2, s14, 64
	v_writelane_b32 v253, s2, 47
	v_writelane_b32 v253, s14, 48
	s_add_i32 s2, s14, 0x80
	v_writelane_b32 v253, s2, 49
	s_lshl_b64 s[2:3], s[0:1], 20
	v_writelane_b32 v253, s2, 50
	s_nop 1
	v_writelane_b32 v253, s3, 51
	s_add_u32 s2, s94, 0x13a00000
	v_writelane_b32 v253, s2, 52
	s_addc_u32 s2, s95, 0
	v_writelane_b32 v253, s2, 53
	s_add_u32 s2, s94, 0x16a00000
	v_writelane_b32 v253, s2, 54
	s_addc_u32 s2, s95, 0
	v_writelane_b32 v253, s2, 55
	s_lshr_b32 s2, s5, 26
	s_add_i32 s2, s4, s2
	s_and_b32 s3, s2, 0x3ffffc0
	s_sub_i32 s3, s4, s3
	s_ashr_i32 s4, s2, 6
	s_lshr_b32 s2, s2, 31
	s_add_i32 s2, s4, s2
	s_and_b32 s2, s2, 0x3fffffe
	s_sub_i32 s2, s4, s2
	s_lshl_b32 s2, s2, 6
	s_lshl_b32 s4, s3, 6
	s_ashr_i32 s3, s2, 31
	s_lshl_b64 s[2:3], s[2:3], 1
	s_add_u32 s14, s6, s2
	v_writelane_b32 v253, s6, 56
	s_addc_u32 s15, s7, s3
	s_add_u32 s2, s8, s2
	v_writelane_b32 v253, s7, 57
	v_writelane_b32 v253, s14, 58
	s_nop 1
	v_writelane_b32 v253, s15, 59
	v_writelane_b32 v253, s8, 60
	s_addc_u32 s3, s9, s3
	s_lshl_b64 s[0:1], s[0:1], 19
	v_writelane_b32 v251, s0, 0
	v_writelane_b32 v253, s9, 61
	v_writelane_b32 v253, s2, 62
	v_writelane_b32 v251, s1, 1
	s_add_i32 s0, s4, 0xffffff80
	v_writelane_b32 v251, s0, 2
	v_writelane_b32 v251, s4, 3
	s_sub_i32 s0, s4, 64
	v_writelane_b32 v251, s0, 4
	s_add_u32 s0, s94, 0x1ca00000
	s_addc_u32 s1, s95, 0
	v_writelane_b32 v251, s0, 5
	s_cmpk_lt_i32 s68, 0x200
	v_writelane_b32 v253, s3, 63
	v_writelane_b32 v251, s1, 6
	s_cselect_b64 s[0:1], -1, 0
	v_writelane_b32 v251, s0, 7
	s_nop 1
	v_writelane_b32 v251, s1, 8
	s_lshl_b32 s0, s13, 6
	s_cmp_lt_i32 s13, 0
	s_mul_i32 s1, s13, 0x41
	s_cselect_b32 s0, s1, s0
	s_add_i32 s0, s0, s12
	s_ashr_i32 s1, s0, 31
	s_lshr_b32 s1, s1, 28
	s_add_i32 s1, s0, s1
	s_and_b32 s2, s1, 0xfff0
	s_sub_i32 s0, s0, s2
	s_bfe_i32 s2, s0, 0x80000
	s_bfe_u32 s2, s2, 0x2000d
	s_add_i32 s2, s0, s2
	s_and_b32 s3, s2, 0xfc
	s_sub_i32 s0, s0, s3
	s_ashr_i32 s1, s1, 4
	s_bfe_i32 s2, s2, 0x80000
	s_lshl_b32 s1, s1, 2
	s_sext_i32_i16 s2, s2
	s_sext_i32_i8 s0, s0
	v_writelane_b32 v251, s12, 9
	s_add_i32 s4, s1, s0
	s_ashr_i32 s0, s2, 2
	v_writelane_b32 v251, s0, 10
	s_lshr_b32 s0, s2, 2
	s_bfe_i64 s[0:1], s[0:1], 0x100000
	s_lshl_b64 s[0:1], s[0:1], 19
	v_writelane_b32 v251, s0, 11
	s_ashr_i32 s5, s4, 31
	s_nop 0
	v_writelane_b32 v251, s1, 12
	v_writelane_b32 v251, s13, 13
	s_lshr_b32 s0, s13, 31
	v_writelane_b32 v251, s0, 14
	s_mov_b32 s0, s4
	v_writelane_b32 v251, s0, 15
	s_nop 1
	v_writelane_b32 v251, s1, 16
	s_lshl_b64 s[0:1], s[4:5], 19
	s_add_u32 s2, s10, s0
	v_writelane_b32 v251, s10, 17
	s_mul_i32 s0, s81, s80
	s_mul_i32 s0, s0, s33
	v_writelane_b32 v251, s11, 18
	s_addc_u32 s3, s11, s1
	v_writelane_b32 v251, s0, 19
	s_add_u32 s0, s2, 0x40000
	v_writelane_b32 v251, s2, 20
	s_addc_u32 s1, s3, 0
	s_nop 0
	v_writelane_b32 v251, s3, 21
	v_writelane_b32 v251, s0, 22
	s_nop 1
	v_writelane_b32 v251, s1, 23
	s_add_u32 s0, s94, 0xea00040
	s_addc_u32 s1, s95, 0
	v_writelane_b32 v251, s0, 24
	s_add_i32 s2, 0, 0x25fc0
	s_nop 0
	v_writelane_b32 v251, s1, 25
	v_writelane_b32 v251, s2, 26
	s_add_i32 s2, 0, 0x25fc4
	v_writelane_b32 v251, s2, 27
	v_writelane_b32 v251, s68, 28
	v_writelane_b32 v251, s72, 29
	s_mov_b32 s1, 0
	s_mov_b32 s0, s1
	v_writelane_b32 v251, s73, 30
	v_writelane_b32 v251, s74, 31
	v_writelane_b32 v251, s75, 32
	v_writelane_b32 v251, s76, 33
	v_writelane_b32 v251, s77, 34
	v_writelane_b32 v251, s78, 35
	v_writelane_b32 v251, s79, 36
	v_writelane_b32 v251, s92, 37
	s_mov_b64 s[2:3], 0x80
	s_nop 0
	v_writelane_b32 v251, s93, 38
	v_writelane_b32 v251, s94, 39
	v_writelane_b32 v251, s95, 40
	v_writelane_b32 v251, s80, 41
	s_nop 1
	v_writelane_b32 v251, s81, 42
	v_writelane_b32 v251, s70, 43
	s_nop 1
	v_writelane_b32 v251, s71, 44
	v_writelane_b32 v251, s88, 45
	s_nop 1
	v_writelane_b32 v251, s89, 46
	v_writelane_b32 v251, s82, 47
	s_nop 1
	v_writelane_b32 v251, s83, 48
	v_writelane_b32 v251, s91, 49
	v_readlane_b32 s96, v252, 25
	v_readlane_b32 s97, v252, 26
	s_add_u32 s96, s96, 0x3600
	s_addc_u32 s97, s97, 0
	v_mbcnt_lo_u32_b32 v248, -1, 0
	v_mbcnt_hi_u32_b32 v248, -1, v248
	v_and_b32_e32 v248, 7, v248
	v_lshlrev_b32_e32 v248, 2, v248
	global_load_dword v249, v248, s[96:97] sc1
	global_load_dword v248, v248, s[96:97] offset:32 sc1
	s_waitcnt vmcnt(0)
	v_add_u32_e32 v248, v248, v249
	v_cmp_ne_u32_e32 vcc, 17, v248
	s_cmp_lg_u64 vcc, 0
	s_cselect_b32 s96, 1, 0
	s_cmp_lg_u32 s80, 0x100
	s_cselect_b32 s97, 1, 0
	s_or_b32 s96, s96, s97
	v_writelane_b32 v250, s96, 63
	s_nop 0
	s_branch .LBB0_281
